# coalesced epilogues: E1 L0+L2 (LDS transpose, remap) and O3 L3 (swapped MFMA layout)
# baseline (speedup 1.0000x reference)
; #define PG8_WAIT_V(n) asm volatile("s_waitcnt vmcnt(" #n ")" ::: "memory")
; template <class Epi, class Sched>
; __device__ __forceinline__ void gemm_phase(LAS unsigned char* lds, const int K, const int lda, const int ldb, const Sched& S, const Epi& E) {
;     ...
;     const int aoff = lds_byte(wr * 64 + fr, fq * 8), boff = lds_byte(wc * 32 + fr, fq * 8);
;     ...
;     Unit cur, nxt; int ui = 0;
;     if (!S.next(0, cur)) return;
;     f32x4 acc[2][2][4][2];
; #pragma unroll
;     for (int a = 0; a < 2; ++a)
; #pragma unroll
;         for (int b = 0; b < 2; ++b)
; #pragma unroll
;             for (int m = 0; m < 4; ++m)
; #pragma unroll
;                 for (int n = 0; n < 2; ++n) acc[a][b][m][n] = (f32x4){0.f, 0.f, 0.f, 0.f};
;     bf16x8 At[4][2], B0[2][2], B1[2][2];
;     const char* cA = S.aptr(cur); const char* cB = S.bptr(cur);
;     PG8_STAGE(PG8_SB(0, 0), cB, voffB); PG8_STAGE(PG8_SB(0, 1), cB + hB, voffB); PG8_STAGE(PG8_SA(0, 0), cA, voffA); PG8_STAGE(PG8_SA(0, 1), cA + hA, voffA);
;     if (wr == 1) PG8_BAR;
;     PG8_WAIT_V(2); PG8_BAR;
;     PG8_STAGE(PG8_SB(1, 0), cB + kstep, voffB); PG8_STAGE(PG8_SA(1, 0), cA + kstep, voffA); PG8_STAGE(PG8_SB(1, 1), cB + hB + kstep, voffB);
;     PG8_WAIT_V(6); PG8_BAR;
;     __device__ __forceinline__ void operator()(const f32x4 (&acc)[2][2][4][2], const Unit& u, int wr, int wc, int fr, int fq, LAS unsigned char* xs, int wid, int lane) const {
;     ...
;             for (int ai = 0; ai < 2; ++ai)
; #pragma unroll
;                 for (int bj = 0; bj < 2; ++bj) {
;                     f32x4 v[4][2];
; #pragma unroll
;                     for (int m = 0; m < 4; ++m) { v[m][0] = acc[ai][bj][m][0] * rs[ai][m]; v[m][1] = acc[ai][bj][m][1] * rs[ai][m]; }
;                     if (ODD) {
;                         float* vss = (float*)(ws + OFF_VSS);
; #pragma unroll
;                         for (int m = 0; m < 4; ++m) {
;                             float s = 0.f;
; #pragma unroll
;                             for (int n = 0; n < 2; ++n) s += (v[m][n][0] * v[m][n][0] + v[m][n][1] * v[m][n][1]) + (v[m][n][2] * v[m][n][2] + v[m][n][3] * v[m][n][3]);
;                             s += __shfl_xor(s, 16); s += __shfl_xor(s, 32);
;                             if (fq == 0) vss[(size_t)(row0 + ai * 128 + m * 16 + fr) * 32 + (2 * (pn - 24) + bj) * 4 + wc] = s;
;                         }
;                     }
.LBB0_957:
	s_sext_i32_i16 s0, s8
	v_and_b32_e32 v157, 15, v10
	s_and_b32 s8, s18, 3
	v_and_b32_e32 v17, 48, v10
	v_lshlrev_b32_e32 v18, 2, v10
	s_mov_b64 s[50:51], 0x80
	s_lshl_b32 s15, s17, 6
	s_lshl_b32 s11, s17, 13
	v_lshl_or_b32 v17, v157, 6, v17
	v_and_b32_e32 v18, 32, v18
	s_lshl_b32 s17, s8, 13
	s_add_i32 m0, s1, 0x18000
	v_lshl_add_u64 v[6:7], v[6:7], 0, s[50:51]
	v_bitop3_b32 v19, v17, s11, v18 bitop3:0xde
	s_lshl_b32 s11, s8, 5
	v_bitop3_b32 v161, v17, s17, v18 bitop3:0xde
	s_waitcnt vmcnt(2)
	s_barrier
	global_load_lds_dwordx4 v[6:7], off
	v_lshl_add_u64 v[4:5], v[4:5], 0, s[50:51]
	s_add_i32 m0, s1, 0x1a000
	s_add_i32 s17, s1, 0x8000
	s_add_i32 s21, s1, 0xa000
	global_load_lds_dwordx4 v[4:5], off
	v_lshl_add_u64 v[0:1], v[0:1], 0, s[50:51]
	s_mov_b32 m0, s17
	s_add_u32 s24, s66, 0x80080
	global_load_lds_dwordx4 v[0:1], off
	v_lshl_add_u64 v[0:1], v[2:3], 0, s[50:51]
	s_mov_b32 m0, s21
	s_addc_u32 s25, s67, 0
	global_load_lds_dwordx4 v[0:1], off
	s_add_i32 m0, s1, 0x1c000
	v_lshl_add_u64 v[0:1], s[24:25], 0, v[132:133]
	global_load_lds_dwordx4 v[0:1], off
	v_lshl_add_u64 v[0:1], s[24:25], 0, v[128:129]
	s_add_i32 m0, s1, 0x1e000
	s_cmpk_lt_u32 s9, 0x100
	global_load_lds_dwordx4 v[0:1], off
	v_lshlrev_b32_e32 v26, 15, v8
	s_cselect_b64 s[52:53], -1, 0
	s_lshl_b32 s9, s18, 12
	v_and_b32_e32 v26, 0xffff0000, v26
	s_add_i32 s9, s9, 0
	v_lshl_add_u32 v9, v9, 12, v26
	v_and_b32_e32 v8, 1, v8
	s_add_i32 s9, s9, 0x20000
	v_lshl_or_b32 v8, v8, 6, v9
	s_add_u32 s23, s48, 0x1ce00000
	v_lshlrev_b32_e32 v0, 1, v10
	v_lshl_add_u32 v138, v11, 1, v8
	v_lshlrev_b32_e32 v8, 15, v13
	v_bfe_u32 v15, v10, 4, 2
	s_addc_u32 s24, s49, 0
	v_and_b32_e32 v0, 14, v0
	v_bfe_u32 v2, v10, 3, 1
	v_and_b32_e32 v8, 0xffff0000, v8
	s_add_u32 s25, s48, 0x14e00000
	v_add_u32_e32 v0, s9, v0
	v_bitop3_b32 v4, v2, v15, 2 bitop3:0x36
	v_lshl_add_u32 v8, v12, 12, v8
	v_and_b32_e32 v9, 1, v13
	s_addc_u32 s26, s49, 0
	v_xor_b32_e32 v3, v2, v15
	v_lshl_add_u32 v5, v4, 4, v0
	v_bitop3_b32 v4, v2, v15, 4 bitop3:0x36
	v_bitop3_b32 v2, v2, v15, 6 bitop3:0x36
	v_lshl_or_b32 v8, v9, 6, v8
	v_and_b32_e32 v159, 63, v10
	v_lshlrev_b32_e32 v16, 3, v15
	s_add_u32 s27, s48, 0xae00000
	v_lshlrev_b32_e32 v1, 10, v15
	v_lshl_add_u32 v15, v2, 4, v0
	v_and_b32_e32 v2, 7, v10
	v_bfe_u32 v10, v10, 3, 3
	v_lshl_add_u32 v140, v14, 1, v8
	v_mbcnt_lo_u32_b32 v8, -1, 0
	s_waitcnt vmcnt(6)
	s_addc_u32 s28, s49, 0
	s_lshl_b32 s8, s8, 21
	v_lshl_add_u32 v3, v3, 4, v0
	v_lshl_add_u32 v7, v4, 4, v0
	v_lshlrev_b32_e32 v0, 3, v2
	v_lshl_add_u32 v17, v10, 7, s9
	v_lshlrev_b32_e32 v18, 4, v2
	v_lshlrev_b32_e32 v2, 15, v10
	v_or_b32_e32 v4, 8, v10
	v_or_b32_e32 v6, 16, v10
	v_or_b32_e32 v10, 24, v10
	v_mbcnt_hi_u32_b32 v8, -1, v8
	v_lshl_add_u32 v20, v4, 7, s9
	v_xor_b32_e32 v21, 16, v18
	v_lshlrev_b32_e32 v4, 15, v4
	v_lshl_add_u32 v22, v6, 7, s9
	v_xor_b32_e32 v23, 32, v18
	v_lshlrev_b32_e32 v6, 15, v6
	v_lshl_add_u32 v24, v10, 7, s9
	v_xor_b32_e32 v25, 48, v18
	v_lshlrev_b32_e32 v10, 15, v10
	s_or_b32 s9, s8, 0x100000
	s_add_i32 s30, 0, 0x10000
	s_add_i32 s31, 0, 0x14000
	v_and_or_b32 v8, v8, 64, v157
	s_ashr_i32 s29, s3, 31
	v_mov_b32_e32 v139, v137
	v_mov_b32_e32 v141, v137
	v_add_u32_e32 v163, 0, v19
	v_lshlrev_b32_e32 v165, 2, v8
	s_mov_b32 s34, 0x800000
	v_lshlrev_b32_e32 v136, 1, v0
	v_add_u32_e32 v167, v3, v1
	v_add_u32_e32 v169, v5, v1
	v_add_u32_e32 v171, v7, v1
	v_add_u32_e32 v173, v15, v1
	s_lshl_b32 s54, s8, 1
	v_add_u32_e32 v184, v17, v18
	v_lshlrev_b32_e32 v142, 1, v2
	v_add_u32_e32 v185, v20, v21
	v_lshlrev_b32_e32 v144, 1, v4
	v_add_u32_e32 v186, v22, v23
	v_lshlrev_b32_e32 v146, 1, v6
	v_add_u32_e32 v187, v24, v25
	v_lshlrev_b32_e32 v148, 1, v10
	s_lshl_b32 s56, s9, 1
	s_lshl_b32 s35, s11, 1
	v_lshlrev_b32_e32 v150, 1, v16
	v_mov_b64_e32 v[152:153], 0xa00
	v_mov_b64_e32 v[154:155], 0x9ff
	v_add_u32_e32 v188, s30, v161
	v_add_u32_e32 v189, 0x11000, v161
	v_mov_b32_e32 v156, 0x358637bd
	s_mov_b32 s38, 0
	s_barrier
	s_branch .LBB0_960

; #define PG8_STAGE(bufoff, gbase, voff) do { _Pragma("unroll") for (int _i = 0; _i < 2; ++_i) \
;         __builtin_amdgcn_global_load_lds((const unsigned*)((const char*)(gbase) + (voff)[_i]), (LAS unsigned*)(lds + (bufoff) + ldsw + _i * 8192), 16, 0, 0); } while (0)
; #define PG8_LDA(dst, b, h) do { _Pragma("unroll") for (int m = 0; m < 4; ++m) _Pragma("unroll") for (int k = 0; k < 2; ++k) dst[m][k] = *(const LAS bf16x8*)(lds + PG8_SA(b, h) + aoff + m * 2048 + k * 1024); } while (0)
; #define PG8_LDB(dst, b, h) do { _Pragma("unroll") for (int n = 0; n < 2; ++n) _Pragma("unroll") for (int k = 0; k < 2; ++k) dst[n][k] = *(const LAS bf16x8*)(lds + PG8_SB(b, h) + boff + n * 2048 + k * 1024); } while (0)
; #define PG8_MMA(ai, bj, At, Bt) do { __builtin_amdgcn_s_setprio(1); _Pragma("unroll") for (int m = 0; m < 4; ++m) _Pragma("unroll") for (int n = 0; n < 2; ++n) _Pragma("unroll") for (int k = 0; k < 2; ++k) \
;         acc[ai][bj][m][n] = __builtin_amdgcn_mfma_f32_16x16x32_bf16(Bt[n][k], At[m][k], acc[ai][bj][m][n], 0, 0, 0); __builtin_amdgcn_s_setprio(0); } while (0)
; #define PG8_WAIT_V(n) asm volatile("s_waitcnt vmcnt(" #n ")" ::: "memory")
; #define PG8_WAIT_L(n) asm volatile("s_waitcnt lgkmcnt(" #n ")" ::: "memory")
; #define PG8_BAR __builtin_amdgcn_s_barrier()
; #define PG8_SCHED __builtin_amdgcn_sched_barrier(0)
; template <class Epi, class Sched>
; __device__ __forceinline__ void gemm_phase(LAS unsigned char* lds, const int K, const int lda, const int ldb, const Sched& S, const Epi& E) {
;     ...
;             PG8_LDB(B0, 0, 0); PG8_LDB(B1, 0, 1); PG8_SCHED; PG8_LDA(At, 0, 0); PG8_STAGE(PG8_SA(1, 1), a1 + hA, voffA);
;             PG8_WAIT_V(8); PG8_WAIT_L(0); PG8_BAR; PG8_MMA(0, 0, At, B0); PG8_MMA(0, 1, At, B1); PG8_BAR; PG8_SCHED;
;             PG8_LDA(At, 0, 1); PG8_STAGE(PG8_SB(0, 0), b2, voffB); PG8_STAGE(PG8_SB(0, 1), b2 + hB, voffB); PG8_STAGE(PG8_SA(0, 0), a2, voffA);
;             PG8_WAIT_V(8); PG8_WAIT_L(0); PG8_BAR; PG8_MMA(1, 0, At, B0); PG8_MMA(1, 1, At, B1); PG8_BAR; PG8_SCHED;
.LBB0_963:
	ds_read_b128 v[174:177], v188
	ds_read_b128 v[178:181], v188 offset:1024
	ds_read_b128 v[190:193], v188 offset:2048
	ds_read_b128 v[194:197], v188 offset:3072
	ds_read_b128 v[198:201], v189
	ds_read_b128 v[202:205], v189 offset:1024
	ds_read_b128 v[206:209], v189 offset:2048
	ds_read_b128 v[210:213], v189 offset:3072
	s_add_u32 s61, s66, 0xfff80080
	s_addc_u32 s68, s67, -1
	s_cmp_eq_u32 s59, 28
	s_cselect_b32 s71, s11, s68
	s_cselect_b32 s70, s18, s61
	s_cselect_b32 s69, s39, s57
	s_cselect_b32 s68, s41, s55
	v_lshl_add_u64 v[182:183], s[66:67], 0, v[140:141]
	s_add_i32 m0, s1, 0xc000
	ds_read_b128 v[214:217], v163
	ds_read_b128 v[218:221], v163 offset:1024
	ds_read_b128 v[222:225], v163 offset:2048
	ds_read_b128 v[226:229], v163 offset:3072
	ds_read_b128 v[230:233], v163 offset:4096
	ds_read_b128 v[236:239], v163 offset:5120
	ds_read_b128 v[240:243], v163 offset:6144
	ds_read_b128 v[244:247], v163 offset:7168
	global_load_lds_dwordx4 v[182:183], off
	v_lshl_add_u64 v[182:183], s[66:67], 0, v[138:139]
	s_add_i32 m0, s1, 0xe000
	s_nop 0
	global_load_lds_dwordx4 v[182:183], off
	s_waitcnt vmcnt(8)
	s_waitcnt lgkmcnt(0)
	s_barrier
	s_setprio 1
	s_waitcnt lgkmcnt(0)
	v_mfma_f32_16x16x32_bf16 v[124:127], v[174:177], v[214:217], v[124:127]
	v_mfma_f32_16x16x32_bf16 v[120:123], v[190:193], v[214:217], v[120:123]
	v_mfma_f32_16x16x32_bf16 v[108:111], v[174:177], v[222:225], v[108:111]
	v_mfma_f32_16x16x32_bf16 v[104:107], v[190:193], v[222:225], v[104:107]
	v_mfma_f32_16x16x32_bf16 v[92:95], v[174:177], v[230:233], v[92:95]
	v_mfma_f32_16x16x32_bf16 v[88:91], v[190:193], v[230:233], v[88:91]
	v_mfma_f32_16x16x32_bf16 v[76:79], v[174:177], v[240:243], v[76:79]
	v_mfma_f32_16x16x32_bf16 v[72:75], v[190:193], v[240:243], v[72:75]
	v_mfma_f32_16x16x32_bf16 v[124:127], v[178:181], v[218:221], v[124:127]
	v_mfma_f32_16x16x32_bf16 v[120:123], v[194:197], v[218:221], v[120:123]
	v_mfma_f32_16x16x32_bf16 v[108:111], v[178:181], v[226:229], v[108:111]
	v_mfma_f32_16x16x32_bf16 v[104:107], v[194:197], v[226:229], v[104:107]
	v_mfma_f32_16x16x32_bf16 v[92:95], v[178:181], v[236:239], v[92:95]
	v_mfma_f32_16x16x32_bf16 v[88:91], v[194:197], v[236:239], v[88:91]
	v_mfma_f32_16x16x32_bf16 v[76:79], v[178:181], v[244:247], v[76:79]
	v_mfma_f32_16x16x32_bf16 v[72:75], v[194:197], v[244:247], v[72:75]
	s_setprio 0
	s_setprio 1
	v_mfma_f32_16x16x32_bf16 v[116:119], v[198:201], v[214:217], v[116:119]
	v_mfma_f32_16x16x32_bf16 v[112:115], v[206:209], v[214:217], v[112:115]
	v_mfma_f32_16x16x32_bf16 v[100:103], v[198:201], v[222:225], v[100:103]
	v_mfma_f32_16x16x32_bf16 v[96:99], v[206:209], v[222:225], v[96:99]
	v_mfma_f32_16x16x32_bf16 v[84:87], v[198:201], v[230:233], v[84:87]
	v_mfma_f32_16x16x32_bf16 v[80:83], v[206:209], v[230:233], v[80:83]
	v_mfma_f32_16x16x32_bf16 v[68:71], v[198:201], v[240:243], v[68:71]
	v_mfma_f32_16x16x32_bf16 v[64:67], v[206:209], v[240:243], v[64:67]
	v_mfma_f32_16x16x32_bf16 v[116:119], v[202:205], v[218:221], v[116:119]
	v_mfma_f32_16x16x32_bf16 v[112:115], v[210:213], v[218:221], v[112:115]
	v_mfma_f32_16x16x32_bf16 v[100:103], v[202:205], v[226:229], v[100:103]
	v_mfma_f32_16x16x32_bf16 v[96:99], v[210:213], v[226:229], v[96:99]
	v_mfma_f32_16x16x32_bf16 v[84:87], v[202:205], v[236:239], v[84:87]
	v_mfma_f32_16x16x32_bf16 v[80:83], v[210:213], v[236:239], v[80:83]
	v_mfma_f32_16x16x32_bf16 v[68:71], v[202:205], v[244:247], v[68:71]
	v_mfma_f32_16x16x32_bf16 v[64:67], v[210:213], v[244:247], v[64:67]
	s_setprio 0
	s_barrier
	s_add_i32 s61, s30, s2
	v_lshl_add_u64 v[182:183], s[68:69], 0, v[132:133]
	s_mov_b32 m0, s61
	ds_read_b128 v[214:217], v163 offset:16384
	ds_read_b128 v[218:221], v163 offset:17408
	ds_read_b128 v[222:225], v163 offset:18432
	ds_read_b128 v[226:229], v163 offset:19456
	ds_read_b128 v[230:233], v163 offset:20480
	ds_read_b128 v[236:239], v163 offset:21504
	ds_read_b128 v[240:243], v163 offset:22528
	ds_read_b128 v[244:247], v163 offset:23552
	global_load_lds_dwordx4 v[182:183], off
	s_add_i32 m0, s61, 0x2000
	s_add_u32 s72, s68, 0x80000
	v_lshl_add_u64 v[234:235], s[68:69], 0, v[128:129]
	s_addc_u32 s73, s69, 0
	s_add_i32 s61, s31, s2
	global_load_lds_dwordx4 v[234:235], off
	v_lshl_add_u64 v[248:249], s[72:73], 0, v[132:133]
	s_mov_b32 m0, s61
	v_lshl_add_u64 v[250:251], s[70:71], 0, v[130:131]
	global_load_lds_dwordx4 v[248:249], off
	v_lshl_add_u64 v[248:249], s[72:73], 0, v[128:129]
	s_add_i32 m0, s61, 0x2000
	s_nop 0
	global_load_lds_dwordx4 v[248:249], off
	v_lshl_add_u64 v[248:249], s[70:71], 0, v[134:135]
	s_mov_b32 m0, s1
	s_nop 0
	global_load_lds_dwordx4 v[248:249], off
	s_mov_b32 m0, s6
	s_nop 0
	global_load_lds_dwordx4 v[250:251], off
	s_waitcnt vmcnt(8)
	s_waitcnt lgkmcnt(0)
	s_barrier
; #define PG8_STAGE(bufoff, gbase, voff) do { _Pragma("unroll") for (int _i = 0; _i < 2; ++_i) \
;         __builtin_amdgcn_global_load_lds((const unsigned*)((const char*)(gbase) + (voff)[_i]), (LAS unsigned*)(lds + (bufoff) + ldsw + _i * 8192), 16, 0, 0); } while (0)
; #define PG8_LDA(dst, b, h) do { _Pragma("unroll") for (int m = 0; m < 4; ++m) _Pragma("unroll") for (int k = 0; k < 2; ++k) dst[m][k] = *(const LAS bf16x8*)(lds + PG8_SA(b, h) + aoff + m * 2048 + k * 1024); } while (0)
; #define PG8_LDB(dst, b, h) do { _Pragma("unroll") for (int n = 0; n < 2; ++n) _Pragma("unroll") for (int k = 0; k < 2; ++k) dst[n][k] = *(const LAS bf16x8*)(lds + PG8_SB(b, h) + boff + n * 2048 + k * 1024); } while (0)
; #define PG8_MMA(ai, bj, At, Bt) do { __builtin_amdgcn_s_setprio(1); _Pragma("unroll") for (int m = 0; m < 4; ++m) _Pragma("unroll") for (int n = 0; n < 2; ++n) _Pragma("unroll") for (int k = 0; k < 2; ++k) \
;         acc[ai][bj][m][n] = __builtin_amdgcn_mfma_f32_16x16x32_bf16(Bt[n][k], At[m][k], acc[ai][bj][m][n], 0, 0, 0); __builtin_amdgcn_s_setprio(0); } while (0)
; #define PG8_WAIT_V(n) asm volatile("s_waitcnt vmcnt(" #n ")" ::: "memory")
; #define PG8_WAIT_L(n) asm volatile("s_waitcnt lgkmcnt(" #n ")" ::: "memory")
; #define PG8_BAR __builtin_amdgcn_s_barrier()
; #define PG8_SCHED __builtin_amdgcn_sched_barrier(0)
; template <class Epi, class Sched>
; __device__ __forceinline__ void gemm_phase(LAS unsigned char* lds, const int K, const int lda, const int ldb, const Sched& S, const Epi& E) {
;     ...
;             PG8_WAIT_V(8); PG8_WAIT_L(0); PG8_BAR; PG8_MMA(1, 0, At, B0); PG8_MMA(1, 1, At, B1); PG8_BAR; PG8_SCHED;
;             PG8_LDB(B0, 1, 0); PG8_LDB(B1, 1, 1); PG8_SCHED; PG8_LDA(At, 1, 0); PG8_STAGE(PG8_SA(0, 1), a2 + hA, voffA);
;             PG8_WAIT_V(8); PG8_WAIT_L(0); PG8_BAR; PG8_MMA(0, 0, At, B0); PG8_MMA(0, 1, At, B1); PG8_BAR; PG8_SCHED;
;             PG8_LDA(At, 1, 1); PG8_STAGE(PG8_SB(1, 0), b3, voffB); PG8_STAGE(PG8_SB(1, 1), b3 + hB, voffB); PG8_STAGE(PG8_SA(1, 0), a3, voffA);
	s_setprio 1
	s_waitcnt lgkmcnt(0)
	v_mfma_f32_16x16x32_bf16 v[60:63], v[174:177], v[214:217], v[60:63]
	v_mfma_f32_16x16x32_bf16 v[56:59], v[190:193], v[214:217], v[56:59]
	v_mfma_f32_16x16x32_bf16 v[44:47], v[174:177], v[222:225], v[44:47]
	v_mfma_f32_16x16x32_bf16 v[40:43], v[190:193], v[222:225], v[40:43]
	v_mfma_f32_16x16x32_bf16 v[28:31], v[174:177], v[230:233], v[28:31]
	v_mfma_f32_16x16x32_bf16 v[24:27], v[190:193], v[230:233], v[24:27]
	v_mfma_f32_16x16x32_bf16 v[12:15], v[174:177], v[240:243], v[12:15]
	v_mfma_f32_16x16x32_bf16 v[8:11], v[190:193], v[240:243], v[8:11]
	v_mfma_f32_16x16x32_bf16 v[60:63], v[178:181], v[218:221], v[60:63]
	v_mfma_f32_16x16x32_bf16 v[56:59], v[194:197], v[218:221], v[56:59]
	v_mfma_f32_16x16x32_bf16 v[44:47], v[178:181], v[226:229], v[44:47]
	v_mfma_f32_16x16x32_bf16 v[40:43], v[194:197], v[226:229], v[40:43]
	v_mfma_f32_16x16x32_bf16 v[28:31], v[178:181], v[236:239], v[28:31]
	v_mfma_f32_16x16x32_bf16 v[24:27], v[194:197], v[236:239], v[24:27]
	v_mfma_f32_16x16x32_bf16 v[12:15], v[178:181], v[244:247], v[12:15]
	v_mfma_f32_16x16x32_bf16 v[8:11], v[194:197], v[244:247], v[8:11]
	s_setprio 0
	s_setprio 1
	v_mfma_f32_16x16x32_bf16 v[52:55], v[198:201], v[214:217], v[52:55]
	v_mfma_f32_16x16x32_bf16 v[48:51], v[206:209], v[214:217], v[48:51]
	v_mfma_f32_16x16x32_bf16 v[36:39], v[198:201], v[222:225], v[36:39]
	v_mfma_f32_16x16x32_bf16 v[32:35], v[206:209], v[222:225], v[32:35]
	v_mfma_f32_16x16x32_bf16 v[20:23], v[198:201], v[230:233], v[20:23]
	v_mfma_f32_16x16x32_bf16 v[16:19], v[206:209], v[230:233], v[16:19]
	v_mfma_f32_16x16x32_bf16 v[4:7], v[198:201], v[240:243], v[4:7]
	v_mfma_f32_16x16x32_bf16 v[0:3], v[206:209], v[240:243], v[0:3]
	v_mfma_f32_16x16x32_bf16 v[52:55], v[202:205], v[218:221], v[52:55]
	v_mfma_f32_16x16x32_bf16 v[48:51], v[210:213], v[218:221], v[48:51]
	v_mfma_f32_16x16x32_bf16 v[36:39], v[202:205], v[226:229], v[36:39]
	v_mfma_f32_16x16x32_bf16 v[32:35], v[210:213], v[226:229], v[32:35]
	v_mfma_f32_16x16x32_bf16 v[20:23], v[202:205], v[236:239], v[20:23]
	v_mfma_f32_16x16x32_bf16 v[16:19], v[210:213], v[236:239], v[16:19]
	v_mfma_f32_16x16x32_bf16 v[4:7], v[202:205], v[244:247], v[4:7]
	v_mfma_f32_16x16x32_bf16 v[0:3], v[210:213], v[244:247], v[0:3]
	s_setprio 0
	s_barrier
	s_add_i32 s61, 0, 0x18000
	v_add_u32_e32 v143, s61, v161
	s_add_i32 s72, 0, 0x1c000
	ds_read_b128 v[174:177], v143
	ds_read_b128 v[178:181], v143 offset:1024
	ds_read_b128 v[190:193], v143 offset:2048
	ds_read_b128 v[194:197], v143 offset:3072
	v_add_u32_e32 v143, 0x19000, v161
	ds_read_b128 v[198:201], v143
	ds_read_b128 v[202:205], v143 offset:1024
	ds_read_b128 v[206:209], v143 offset:2048
	ds_read_b128 v[210:213], v143 offset:3072
	s_add_u32 s70, s70, 0x80000
	s_addc_u32 s71, s71, 0
	s_mov_b32 m0, s7
	v_lshl_add_u64 v[252:253], s[70:71], 0, v[134:135]
	ds_read_b128 v[214:217], v163 offset:32768
	ds_read_b128 v[218:221], v163 offset:33792
	ds_read_b128 v[222:225], v163 offset:34816
	ds_read_b128 v[226:229], v163 offset:35840
	ds_read_b128 v[230:233], v163 offset:36864
	ds_read_b128 v[236:239], v163 offset:37888
	ds_read_b128 v[240:243], v163 offset:38912
	ds_read_b128 v[244:247], v163 offset:39936
	global_load_lds_dwordx4 v[252:253], off
	v_lshl_add_u64 v[252:253], s[70:71], 0, v[130:131]
	s_mov_b32 m0, s14
	s_nop 0
	global_load_lds_dwordx4 v[252:253], off
	s_waitcnt vmcnt(8)
	s_waitcnt lgkmcnt(0)
	s_barrier
	s_setprio 1
	s_waitcnt lgkmcnt(0)
	v_mfma_f32_16x16x32_bf16 v[124:127], v[174:177], v[214:217], v[124:127]
	v_mfma_f32_16x16x32_bf16 v[120:123], v[190:193], v[214:217], v[120:123]
	v_mfma_f32_16x16x32_bf16 v[108:111], v[174:177], v[222:225], v[108:111]
	v_mfma_f32_16x16x32_bf16 v[104:107], v[190:193], v[222:225], v[104:107]
	v_mfma_f32_16x16x32_bf16 v[92:95], v[174:177], v[230:233], v[92:95]
	v_mfma_f32_16x16x32_bf16 v[88:91], v[190:193], v[230:233], v[88:91]
	v_mfma_f32_16x16x32_bf16 v[76:79], v[174:177], v[240:243], v[76:79]
	v_mfma_f32_16x16x32_bf16 v[72:75], v[190:193], v[240:243], v[72:75]
	v_mfma_f32_16x16x32_bf16 v[124:127], v[178:181], v[218:221], v[124:127]
	v_mfma_f32_16x16x32_bf16 v[120:123], v[194:197], v[218:221], v[120:123]
	v_mfma_f32_16x16x32_bf16 v[108:111], v[178:181], v[226:229], v[108:111]
	v_mfma_f32_16x16x32_bf16 v[104:107], v[194:197], v[226:229], v[104:107]
	v_mfma_f32_16x16x32_bf16 v[92:95], v[178:181], v[236:239], v[92:95]
	v_mfma_f32_16x16x32_bf16 v[88:91], v[194:197], v[236:239], v[88:91]
	v_mfma_f32_16x16x32_bf16 v[76:79], v[178:181], v[244:247], v[76:79]
	v_mfma_f32_16x16x32_bf16 v[72:75], v[194:197], v[244:247], v[72:75]
	s_setprio 0
	s_setprio 1
	v_mfma_f32_16x16x32_bf16 v[116:119], v[198:201], v[214:217], v[116:119]
	v_mfma_f32_16x16x32_bf16 v[112:115], v[206:209], v[214:217], v[112:115]
	v_mfma_f32_16x16x32_bf16 v[100:103], v[198:201], v[222:225], v[100:103]
	v_mfma_f32_16x16x32_bf16 v[96:99], v[206:209], v[222:225], v[96:99]
	v_mfma_f32_16x16x32_bf16 v[84:87], v[198:201], v[230:233], v[84:87]
	v_mfma_f32_16x16x32_bf16 v[80:83], v[206:209], v[230:233], v[80:83]
	v_mfma_f32_16x16x32_bf16 v[68:71], v[198:201], v[240:243], v[68:71]
	v_mfma_f32_16x16x32_bf16 v[64:67], v[206:209], v[240:243], v[64:67]
	v_mfma_f32_16x16x32_bf16 v[116:119], v[202:205], v[218:221], v[116:119]
	v_mfma_f32_16x16x32_bf16 v[112:115], v[210:213], v[218:221], v[112:115]
	v_mfma_f32_16x16x32_bf16 v[100:103], v[202:205], v[226:229], v[100:103]
	v_mfma_f32_16x16x32_bf16 v[96:99], v[210:213], v[226:229], v[96:99]
	v_mfma_f32_16x16x32_bf16 v[84:87], v[202:205], v[236:239], v[84:87]
	v_mfma_f32_16x16x32_bf16 v[80:83], v[210:213], v[236:239], v[80:83]
	v_mfma_f32_16x16x32_bf16 v[68:71], v[202:205], v[244:247], v[68:71]
	v_mfma_f32_16x16x32_bf16 v[64:67], v[210:213], v[244:247], v[64:67]
	s_setprio 0
	s_barrier
; #define PG8_STAGE(bufoff, gbase, voff) do { _Pragma("unroll") for (int _i = 0; _i < 2; ++_i) \
;         __builtin_amdgcn_global_load_lds((const unsigned*)((const char*)(gbase) + (voff)[_i]), (LAS unsigned*)(lds + (bufoff) + ldsw + _i * 8192), 16, 0, 0); } while (0)
; #define PG8_LDA(dst, b, h) do { _Pragma("unroll") for (int m = 0; m < 4; ++m) _Pragma("unroll") for (int k = 0; k < 2; ++k) dst[m][k] = *(const LAS bf16x8*)(lds + PG8_SA(b, h) + aoff + m * 2048 + k * 1024); } while (0)
; #define PG8_LDB(dst, b, h) do { _Pragma("unroll") for (int n = 0; n < 2; ++n) _Pragma("unroll") for (int k = 0; k < 2; ++k) dst[n][k] = *(const LAS bf16x8*)(lds + PG8_SB(b, h) + boff + n * 2048 + k * 1024); } while (0)
; #define PG8_MMA(ai, bj, At, Bt) do { __builtin_amdgcn_s_setprio(1); _Pragma("unroll") for (int m = 0; m < 4; ++m) _Pragma("unroll") for (int n = 0; n < 2; ++n) _Pragma("unroll") for (int k = 0; k < 2; ++k) \
;         acc[ai][bj][m][n] = __builtin_amdgcn_mfma_f32_16x16x32_bf16(Bt[n][k], At[m][k], acc[ai][bj][m][n], 0, 0, 0); __builtin_amdgcn_s_setprio(0); } while (0)
; #define PG8_WAIT_V(n) asm volatile("s_waitcnt vmcnt(" #n ")" ::: "memory")
; #define PG8_WAIT_L(n) asm volatile("s_waitcnt lgkmcnt(" #n ")" ::: "memory")
; #define PG8_BAR __builtin_amdgcn_s_barrier()
; #define PG8_SCHED __builtin_amdgcn_sched_barrier(0)
; template <class Epi, class Sched>
; __device__ __forceinline__ void gemm_phase(LAS unsigned char* lds, const int K, const int lda, const int ldb, const Sched& S, const Epi& E) {
;     ...
;             PG8_LDB(B0, 1, 0); PG8_LDB(B1, 1, 1); PG8_SCHED; PG8_LDA(At, 1, 0); PG8_STAGE(PG8_SA(0, 1), a2 + hA, voffA);
;             PG8_WAIT_V(8); PG8_WAIT_L(0); PG8_BAR; PG8_MMA(0, 0, At, B0); PG8_MMA(0, 1, At, B1); PG8_BAR; PG8_SCHED;
;             PG8_LDA(At, 1, 1); PG8_STAGE(PG8_SB(1, 0), b3, voffB); PG8_STAGE(PG8_SB(1, 1), b3 + hB, voffB); PG8_STAGE(PG8_SA(1, 0), a3, voffA);
;             PG8_WAIT_V(8); PG8_WAIT_L(0); PG8_BAR; PG8_MMA(1, 0, At, B0); PG8_MMA(1, 1, At, B1); PG8_BAR; PG8_SCHED;
;         }
;         if (wr == 0) PG8_BAR;
	s_add_i32 s61, s61, s2
	v_lshl_add_u64 v[182:183], v[182:183], 0, s[50:51]
	s_mov_b32 m0, s61
	ds_read_b128 v[214:217], v163 offset:49152
	ds_read_b128 v[218:221], v163 offset:50176
	ds_read_b128 v[222:225], v163 offset:51200
	ds_read_b128 v[226:229], v163 offset:52224
	ds_read_b128 v[230:233], v163 offset:53248
	ds_read_b128 v[236:239], v163 offset:54272
	ds_read_b128 v[240:243], v163 offset:55296
	ds_read_b128 v[244:247], v163 offset:56320
	global_load_lds_dwordx4 v[182:183], off
	s_add_i32 m0, s61, 0x2000
	s_add_u32 s68, s68, 0x80080
	v_lshl_add_u64 v[182:183], v[234:235], 0, s[50:51]
	s_addc_u32 s69, s69, 0
	s_add_i32 s61, s72, s2
	global_load_lds_dwordx4 v[182:183], off
	v_lshl_add_u64 v[182:183], s[68:69], 0, v[132:133]
	s_mov_b32 m0, s61
	s_nop 0
	global_load_lds_dwordx4 v[182:183], off
	v_lshl_add_u64 v[182:183], s[68:69], 0, v[128:129]
	s_add_i32 m0, s61, 0x2000
	s_nop 0
	global_load_lds_dwordx4 v[182:183], off
	v_lshl_add_u64 v[182:183], v[248:249], 0, s[50:51]
	s_mov_b32 m0, s17
	s_nop 0
	global_load_lds_dwordx4 v[182:183], off
	v_lshl_add_u64 v[182:183], v[250:251], 0, s[50:51]
	s_mov_b32 m0, s21
	s_nop 0
	global_load_lds_dwordx4 v[182:183], off
	s_waitcnt vmcnt(8)
	s_waitcnt lgkmcnt(0)
	s_barrier
	s_setprio 1
	s_waitcnt lgkmcnt(0)
	v_mfma_f32_16x16x32_bf16 v[60:63], v[174:177], v[214:217], v[60:63]
	v_mfma_f32_16x16x32_bf16 v[56:59], v[190:193], v[214:217], v[56:59]
	v_mfma_f32_16x16x32_bf16 v[44:47], v[174:177], v[222:225], v[44:47]
	v_mfma_f32_16x16x32_bf16 v[40:43], v[190:193], v[222:225], v[40:43]
	v_mfma_f32_16x16x32_bf16 v[28:31], v[174:177], v[230:233], v[28:31]
	v_mfma_f32_16x16x32_bf16 v[24:27], v[190:193], v[230:233], v[24:27]
	v_mfma_f32_16x16x32_bf16 v[12:15], v[174:177], v[240:243], v[12:15]
	v_mfma_f32_16x16x32_bf16 v[8:11], v[190:193], v[240:243], v[8:11]
	v_mfma_f32_16x16x32_bf16 v[60:63], v[178:181], v[218:221], v[60:63]
	v_mfma_f32_16x16x32_bf16 v[56:59], v[194:197], v[218:221], v[56:59]
	v_mfma_f32_16x16x32_bf16 v[44:47], v[178:181], v[226:229], v[44:47]
	v_mfma_f32_16x16x32_bf16 v[40:43], v[194:197], v[226:229], v[40:43]
	v_mfma_f32_16x16x32_bf16 v[28:31], v[178:181], v[236:239], v[28:31]
	v_mfma_f32_16x16x32_bf16 v[24:27], v[194:197], v[236:239], v[24:27]
	v_mfma_f32_16x16x32_bf16 v[12:15], v[178:181], v[244:247], v[12:15]
	v_mfma_f32_16x16x32_bf16 v[8:11], v[194:197], v[244:247], v[8:11]
	s_setprio 0
	s_setprio 1
	v_mfma_f32_16x16x32_bf16 v[52:55], v[198:201], v[214:217], v[52:55]
	v_mfma_f32_16x16x32_bf16 v[48:51], v[206:209], v[214:217], v[48:51]
	v_mfma_f32_16x16x32_bf16 v[36:39], v[198:201], v[222:225], v[36:39]
	v_mfma_f32_16x16x32_bf16 v[32:35], v[206:209], v[222:225], v[32:35]
	v_mfma_f32_16x16x32_bf16 v[20:23], v[198:201], v[230:233], v[20:23]
	v_mfma_f32_16x16x32_bf16 v[16:19], v[206:209], v[230:233], v[16:19]
	v_mfma_f32_16x16x32_bf16 v[4:7], v[198:201], v[240:243], v[4:7]
	v_mfma_f32_16x16x32_bf16 v[0:3], v[206:209], v[240:243], v[0:3]
	v_mfma_f32_16x16x32_bf16 v[52:55], v[202:205], v[218:221], v[52:55]
	v_mfma_f32_16x16x32_bf16 v[48:51], v[210:213], v[218:221], v[48:51]
	v_mfma_f32_16x16x32_bf16 v[36:39], v[202:205], v[226:229], v[36:39]
	v_mfma_f32_16x16x32_bf16 v[32:35], v[210:213], v[226:229], v[32:35]
	v_mfma_f32_16x16x32_bf16 v[20:23], v[202:205], v[236:239], v[20:23]
	v_mfma_f32_16x16x32_bf16 v[16:19], v[210:213], v[236:239], v[16:19]
	v_mfma_f32_16x16x32_bf16 v[4:7], v[202:205], v[244:247], v[4:7]
	v_mfma_f32_16x16x32_bf16 v[0:3], v[210:213], v[244:247], v[0:3]
	s_setprio 0
	s_barrier
	s_add_i32 s59, s59, 2
	s_add_u32 s55, s55, 0x100
	s_addc_u32 s57, s57, 0
	s_add_u32 s66, s66, 0x100
	s_addc_u32 s67, s67, 0
	s_cmp_gt_u32 s59, 29
	s_cbranch_scc0 .LBB0_963
	s_and_b64 vcc, exec, s[52:53]
	s_cbranch_vccz .LBB0_966
	s_barrier

; __device__ __forceinline__ unsigned cvt_pk_bf16(float lo, float hi) { unsigned r; asm("v_cvt_pk_bf16_f32 %0, %1, %2" : "=v"(r) : "v"(lo), "v"(hi)); return r; }
;     __device__ __forceinline__ void operator()(const f32x4 (&acc)[2][2][4][2], const Unit& u, int wr, int wc, int fr, int fq, LAS unsigned char* xs, int wid, int lane) const {
;     ...
;         if (mode == 0) {
; #pragma unroll
;             for (int ai = 0; ai < 2; ++ai)
; #pragma unroll
;                 for (int m = 0; m < 4; ++m) {
;                     const float r = rs[ai][m];
;                     bf16_t* rowp = base + (size_t)(row0 + ai * 128 + m * 16 + fr) * ldc + wc * 32 + 8 * fq;
; #pragma unroll
;                     for (int bj = 0; bj < 2; ++bj) { const f32x4 v0 = acc[ai][bj][m][0] * r, v1 = acc[ai][bj][m][1] * r;
;                         u32x4 w; w.x = cvt_pk_bf16(v0[0], v0[1]); w.y = cvt_pk_bf16(v0[2], v0[3]); w.z = cvt_pk_bf16(v1[0], v1[1]); w.w = cvt_pk_bf16(v1[2], v1[3]);
;                         *(u32x4*)(rowp + bj * 128) = w; }
;                     __builtin_amdgcn_sched_barrier(0);
;                 }
.LBB0_985:
	s_lshl_b32 s70, s10, 4
	s_mov_b32 s71, 0
	s_lshl_b32 s72, s10, 5
	s_mov_b32 s73, 0
	s_mul_i32 s74, s10, 0xa0
	s_mov_b32 s75, 0
	v_lshrrev_b32_e32 v174, 3, v159
	v_add_u32_e32 v174, s66, v174
	v_mul_lo_u32 v174, v174, s10
	v_and_b32_e32 v182, 7, v159
	v_lshlrev_b32_e32 v182, 4, v182
	v_lshl_add_u32 v174, v174, 1, v182
	v_lshlrev_b32_e32 v182, 1, v254
	v_and_b32_e32 v182, 0x180, v182
	v_add_u32_e32 v174, v174, v182
	v_mov_b32_e32 v175, 0
	v_lshl_add_u64 v[174:175], s[68:69], 0, v[174:175]
	v_and_b32_e32 v178, 0x1c0, v254
	v_lshlrev_b32_e32 v178, 6, v178
	v_add_u32_e32 v178, 0x20000, v178
	v_lshrrev_b32_e32 v179, 4, v159
	v_and_b32_e32 v182, 7, v157
	v_xor_b32_e32 v179, v179, v182
	v_lshlrev_b32_e32 v179, 4, v179
	v_lshl_add_u32 v179, v157, 7, v179
	v_add_u32_e32 v179, v178, v179
	v_xor_b32_e32 v180, 64, v179
	v_lshrrev_b32_e32 v181, 3, v159
	v_and_b32_e32 v182, 7, v159
	v_xor_b32_e32 v182, v182, v181
	v_lshlrev_b32_e32 v182, 4, v182
	v_lshl_add_u32 v181, v181, 7, v182
	v_add_u32_e32 v181, v178, v181
	s_waitcnt lgkmcnt(0)
	v_pk_mul_f32 v[124:125], v[124:125], v[172:173] op_sel_hi:[1,0]
	v_pk_mul_f32 v[126:127], v[126:127], v[172:173] op_sel_hi:[1,0]
	v_pk_mul_f32 v[120:121], v[120:121], v[172:173] op_sel_hi:[1,0]
	v_pk_mul_f32 v[122:123], v[122:123], v[172:173] op_sel_hi:[1,0]
	v_pk_mul_f32 v[116:117], v[116:117], v[172:173] op_sel_hi:[1,0]
	v_pk_mul_f32 v[118:119], v[118:119], v[172:173] op_sel_hi:[1,0]
	v_pk_mul_f32 v[112:113], v[112:113], v[172:173] op_sel_hi:[1,0]
	v_pk_mul_f32 v[114:115], v[114:115], v[172:173] op_sel_hi:[1,0]
	v_cvt_pk_bf16_f32 v192, v124, v125
	v_cvt_pk_bf16_f32 v193, v126, v127
	v_cvt_pk_bf16_f32 v194, v120, v121
	v_cvt_pk_bf16_f32 v195, v122, v123
	v_cvt_pk_bf16_f32 v196, v116, v117
	v_cvt_pk_bf16_f32 v197, v118, v119
	v_cvt_pk_bf16_f32 v198, v112, v113
	v_cvt_pk_bf16_f32 v199, v114, v115
	ds_write_b128 v179, v[192:195]
	ds_write_b128 v180, v[196:199]
	ds_read_b128 v[208:211], v181
	ds_read_b128 v[212:215], v181 offset:1024
	v_pk_mul_f32 v[108:109], v[108:109], v[170:171] op_sel_hi:[1,0]
	v_pk_mul_f32 v[110:111], v[110:111], v[170:171] op_sel_hi:[1,0]
	v_pk_mul_f32 v[104:105], v[104:105], v[170:171] op_sel_hi:[1,0]
	v_pk_mul_f32 v[106:107], v[106:107], v[170:171] op_sel_hi:[1,0]
	v_pk_mul_f32 v[100:101], v[100:101], v[170:171] op_sel_hi:[1,0]
	v_pk_mul_f32 v[102:103], v[102:103], v[170:171] op_sel_hi:[1,0]
	v_pk_mul_f32 v[96:97], v[96:97], v[170:171] op_sel_hi:[1,0]
	v_pk_mul_f32 v[98:99], v[98:99], v[170:171] op_sel_hi:[1,0]
	v_cvt_pk_bf16_f32 v200, v108, v109
	v_cvt_pk_bf16_f32 v201, v110, v111
	v_cvt_pk_bf16_f32 v202, v104, v105
	v_cvt_pk_bf16_f32 v203, v106, v107
	v_cvt_pk_bf16_f32 v204, v100, v101
	v_cvt_pk_bf16_f32 v205, v102, v103
	v_cvt_pk_bf16_f32 v206, v96, v97
	v_cvt_pk_bf16_f32 v207, v98, v99
	ds_write_b128 v179, v[200:203] offset:2048
	ds_write_b128 v180, v[204:207] offset:2048
	ds_read_b128 v[216:219], v181 offset:2048
	ds_read_b128 v[220:223], v181 offset:3072
	s_waitcnt lgkmcnt(4)
	v_lshl_add_u64 v[176:177], s[70:71], 0, v[174:175]
	global_store_dwordx4 v[174:175], v[208:211], off
	global_store_dwordx4 v[176:177], v[212:215], off
	v_lshl_add_u64 v[174:175], s[72:73], 0, v[174:175]
	v_pk_mul_f32 v[92:93], v[92:93], v[168:169] op_sel_hi:[1,0]
	v_pk_mul_f32 v[94:95], v[94:95], v[168:169] op_sel_hi:[1,0]
	v_pk_mul_f32 v[88:89], v[88:89], v[168:169] op_sel_hi:[1,0]
	v_pk_mul_f32 v[90:91], v[90:91], v[168:169] op_sel_hi:[1,0]
	v_pk_mul_f32 v[84:85], v[84:85], v[168:169] op_sel_hi:[1,0]
	v_pk_mul_f32 v[86:87], v[86:87], v[168:169] op_sel_hi:[1,0]
	v_pk_mul_f32 v[80:81], v[80:81], v[168:169] op_sel_hi:[1,0]
	v_pk_mul_f32 v[82:83], v[82:83], v[168:169] op_sel_hi:[1,0]
	v_cvt_pk_bf16_f32 v192, v92, v93
	v_cvt_pk_bf16_f32 v193, v94, v95
	v_cvt_pk_bf16_f32 v194, v88, v89
	v_cvt_pk_bf16_f32 v195, v90, v91
	v_cvt_pk_bf16_f32 v196, v84, v85
	v_cvt_pk_bf16_f32 v197, v86, v87
	v_cvt_pk_bf16_f32 v198, v80, v81
	v_cvt_pk_bf16_f32 v199, v82, v83
	ds_write_b128 v179, v[192:195]
	ds_write_b128 v180, v[196:199]
	ds_read_b128 v[208:211], v181
	ds_read_b128 v[212:215], v181 offset:1024
	s_waitcnt lgkmcnt(4)
	v_lshl_add_u64 v[176:177], s[70:71], 0, v[174:175]
	global_store_dwordx4 v[174:175], v[216:219], off
	global_store_dwordx4 v[176:177], v[220:223], off
	v_lshl_add_u64 v[174:175], s[72:73], 0, v[174:175]
	v_pk_mul_f32 v[76:77], v[76:77], v[166:167] op_sel_hi:[1,0]
	v_pk_mul_f32 v[78:79], v[78:79], v[166:167] op_sel_hi:[1,0]
	v_pk_mul_f32 v[72:73], v[72:73], v[166:167] op_sel_hi:[1,0]
	v_pk_mul_f32 v[74:75], v[74:75], v[166:167] op_sel_hi:[1,0]
	v_pk_mul_f32 v[68:69], v[68:69], v[166:167] op_sel_hi:[1,0]
	v_pk_mul_f32 v[70:71], v[70:71], v[166:167] op_sel_hi:[1,0]
	v_pk_mul_f32 v[64:65], v[64:65], v[166:167] op_sel_hi:[1,0]
	v_pk_mul_f32 v[66:67], v[66:67], v[166:167] op_sel_hi:[1,0]
	v_cvt_pk_bf16_f32 v200, v76, v77
	v_cvt_pk_bf16_f32 v201, v78, v79
	v_cvt_pk_bf16_f32 v202, v72, v73
	v_cvt_pk_bf16_f32 v203, v74, v75
	v_cvt_pk_bf16_f32 v204, v68, v69
	v_cvt_pk_bf16_f32 v205, v70, v71
	v_cvt_pk_bf16_f32 v206, v64, v65
	v_cvt_pk_bf16_f32 v207, v66, v67
	ds_write_b128 v179, v[200:203] offset:2048
	ds_write_b128 v180, v[204:207] offset:2048
	ds_read_b128 v[216:219], v181 offset:2048
	ds_read_b128 v[220:223], v181 offset:3072
	s_waitcnt lgkmcnt(4)
; __device__ __forceinline__ unsigned cvt_pk_bf16(float lo, float hi) { unsigned r; asm("v_cvt_pk_bf16_f32 %0, %1, %2" : "=v"(r) : "v"(lo), "v"(hi)); return r; }
;     __device__ __forceinline__ void operator()(const f32x4 (&acc)[2][2][4][2], const Unit& u, int wr, int wc, int fr, int fq, LAS unsigned char* xs, int wid, int lane) const {
;     ...
;         if (mode == 0) {
; #pragma unroll
;             for (int ai = 0; ai < 2; ++ai)
; #pragma unroll
;                 for (int m = 0; m < 4; ++m) {
;                     const float r = rs[ai][m];
;                     bf16_t* rowp = base + (size_t)(row0 + ai * 128 + m * 16 + fr) * ldc + wc * 32 + 8 * fq;
; #pragma unroll
;                     for (int bj = 0; bj < 2; ++bj) { const f32x4 v0 = acc[ai][bj][m][0] * r, v1 = acc[ai][bj][m][1] * r;
;                         u32x4 w; w.x = cvt_pk_bf16(v0[0], v0[1]); w.y = cvt_pk_bf16(v0[2], v0[3]); w.z = cvt_pk_bf16(v1[0], v1[1]); w.w = cvt_pk_bf16(v1[2], v1[3]);
;                         *(u32x4*)(rowp + bj * 128) = w; }
;                     __builtin_amdgcn_sched_barrier(0);
;                 }
	v_lshl_add_u64 v[176:177], s[70:71], 0, v[174:175]
	global_store_dwordx4 v[174:175], v[208:211], off
	global_store_dwordx4 v[176:177], v[212:215], off
	v_lshl_add_u64 v[174:175], s[72:73], 0, v[174:175]
	v_pk_mul_f32 v[60:61], v[60:61], v[164:165] op_sel_hi:[1,0]
	v_pk_mul_f32 v[62:63], v[62:63], v[164:165] op_sel_hi:[1,0]
	v_pk_mul_f32 v[56:57], v[56:57], v[164:165] op_sel_hi:[1,0]
	v_pk_mul_f32 v[58:59], v[58:59], v[164:165] op_sel_hi:[1,0]
	v_pk_mul_f32 v[52:53], v[52:53], v[164:165] op_sel_hi:[1,0]
	v_pk_mul_f32 v[54:55], v[54:55], v[164:165] op_sel_hi:[1,0]
	v_pk_mul_f32 v[48:49], v[48:49], v[164:165] op_sel_hi:[1,0]
	v_pk_mul_f32 v[50:51], v[50:51], v[164:165] op_sel_hi:[1,0]
	v_cvt_pk_bf16_f32 v192, v60, v61
	v_cvt_pk_bf16_f32 v193, v62, v63
	v_cvt_pk_bf16_f32 v194, v56, v57
	v_cvt_pk_bf16_f32 v195, v58, v59
	v_cvt_pk_bf16_f32 v196, v52, v53
	v_cvt_pk_bf16_f32 v197, v54, v55
	v_cvt_pk_bf16_f32 v198, v48, v49
	v_cvt_pk_bf16_f32 v199, v50, v51
	ds_write_b128 v179, v[192:195]
	ds_write_b128 v180, v[196:199]
	ds_read_b128 v[208:211], v181
	ds_read_b128 v[212:215], v181 offset:1024
	s_waitcnt lgkmcnt(4)
	v_lshl_add_u64 v[176:177], s[70:71], 0, v[174:175]
	global_store_dwordx4 v[174:175], v[216:219], off
	global_store_dwordx4 v[176:177], v[220:223], off
	v_lshl_add_u64 v[174:175], s[74:75], 0, v[174:175]
	v_pk_mul_f32 v[44:45], v[44:45], v[162:163] op_sel_hi:[1,0]
	v_pk_mul_f32 v[46:47], v[46:47], v[162:163] op_sel_hi:[1,0]
	v_pk_mul_f32 v[40:41], v[40:41], v[162:163] op_sel_hi:[1,0]
	v_pk_mul_f32 v[42:43], v[42:43], v[162:163] op_sel_hi:[1,0]
	v_pk_mul_f32 v[36:37], v[36:37], v[162:163] op_sel_hi:[1,0]
	v_pk_mul_f32 v[38:39], v[38:39], v[162:163] op_sel_hi:[1,0]
	v_pk_mul_f32 v[32:33], v[32:33], v[162:163] op_sel_hi:[1,0]
	v_pk_mul_f32 v[34:35], v[34:35], v[162:163] op_sel_hi:[1,0]
	v_cvt_pk_bf16_f32 v200, v44, v45
	v_cvt_pk_bf16_f32 v201, v46, v47
	v_cvt_pk_bf16_f32 v202, v40, v41
	v_cvt_pk_bf16_f32 v203, v42, v43
	v_cvt_pk_bf16_f32 v204, v36, v37
	v_cvt_pk_bf16_f32 v205, v38, v39
	v_cvt_pk_bf16_f32 v206, v32, v33
	v_cvt_pk_bf16_f32 v207, v34, v35
	ds_write_b128 v179, v[200:203] offset:2048
	ds_write_b128 v180, v[204:207] offset:2048
	ds_read_b128 v[216:219], v181 offset:2048
	ds_read_b128 v[220:223], v181 offset:3072
	s_waitcnt lgkmcnt(4)
	v_lshl_add_u64 v[176:177], s[70:71], 0, v[174:175]
	global_store_dwordx4 v[174:175], v[208:211], off
	global_store_dwordx4 v[176:177], v[212:215], off
	v_lshl_add_u64 v[174:175], s[72:73], 0, v[174:175]
	v_pk_mul_f32 v[28:29], v[28:29], v[160:161] op_sel_hi:[1,0]
	v_pk_mul_f32 v[30:31], v[30:31], v[160:161] op_sel_hi:[1,0]
	v_pk_mul_f32 v[24:25], v[24:25], v[160:161] op_sel_hi:[1,0]
	v_pk_mul_f32 v[26:27], v[26:27], v[160:161] op_sel_hi:[1,0]
	v_pk_mul_f32 v[20:21], v[20:21], v[160:161] op_sel_hi:[1,0]
	v_pk_mul_f32 v[22:23], v[22:23], v[160:161] op_sel_hi:[1,0]
	v_pk_mul_f32 v[16:17], v[16:17], v[160:161] op_sel_hi:[1,0]
	v_pk_mul_f32 v[18:19], v[18:19], v[160:161] op_sel_hi:[1,0]
	v_cvt_pk_bf16_f32 v192, v28, v29
	v_cvt_pk_bf16_f32 v193, v30, v31
	v_cvt_pk_bf16_f32 v194, v24, v25
	v_cvt_pk_bf16_f32 v195, v26, v27
	v_cvt_pk_bf16_f32 v196, v20, v21
	v_cvt_pk_bf16_f32 v197, v22, v23
	v_cvt_pk_bf16_f32 v198, v16, v17
	v_cvt_pk_bf16_f32 v199, v18, v19
	ds_write_b128 v179, v[192:195]
	ds_write_b128 v180, v[196:199]
	ds_read_b128 v[208:211], v181
	ds_read_b128 v[212:215], v181 offset:1024
	s_waitcnt lgkmcnt(4)
	v_lshl_add_u64 v[176:177], s[70:71], 0, v[174:175]
	global_store_dwordx4 v[174:175], v[216:219], off
	global_store_dwordx4 v[176:177], v[220:223], off
	v_lshl_add_u64 v[174:175], s[72:73], 0, v[174:175]
	v_pk_mul_f32 v[12:13], v[12:13], v[158:159] op_sel_hi:[1,0]
	v_pk_mul_f32 v[14:15], v[14:15], v[158:159] op_sel_hi:[1,0]
	v_pk_mul_f32 v[8:9], v[8:9], v[158:159] op_sel_hi:[1,0]
	v_pk_mul_f32 v[10:11], v[10:11], v[158:159] op_sel_hi:[1,0]
	v_pk_mul_f32 v[4:5], v[4:5], v[158:159] op_sel_hi:[1,0]
	v_pk_mul_f32 v[6:7], v[6:7], v[158:159] op_sel_hi:[1,0]
	v_pk_mul_f32 v[0:1], v[0:1], v[158:159] op_sel_hi:[1,0]
	v_pk_mul_f32 v[2:3], v[2:3], v[158:159] op_sel_hi:[1,0]
	v_cvt_pk_bf16_f32 v200, v12, v13
	v_cvt_pk_bf16_f32 v201, v14, v15
	v_cvt_pk_bf16_f32 v202, v8, v9
	v_cvt_pk_bf16_f32 v203, v10, v11
	v_cvt_pk_bf16_f32 v204, v4, v5
	v_cvt_pk_bf16_f32 v205, v6, v7
	v_cvt_pk_bf16_f32 v206, v0, v1
	v_cvt_pk_bf16_f32 v207, v2, v3
	ds_write_b128 v179, v[200:203] offset:2048
	ds_write_b128 v180, v[204:207] offset:2048
	ds_read_b128 v[216:219], v181 offset:2048
	ds_read_b128 v[220:223], v181 offset:3072
	s_waitcnt lgkmcnt(4)
	v_lshl_add_u64 v[176:177], s[70:71], 0, v[174:175]
	global_store_dwordx4 v[174:175], v[208:211], off
	global_store_dwordx4 v[176:177], v[212:215], off
	v_lshl_add_u64 v[174:175], s[72:73], 0, v[174:175]
	s_waitcnt lgkmcnt(0)
	v_lshl_add_u64 v[176:177], s[70:71], 0, v[174:175]
	global_store_dwordx4 v[174:175], v[216:219], off
	global_store_dwordx4 v[176:177], v[220:223], off
	s_andn2_b64 vcc, exec, s[8:9]
	s_mov_b64 s[8:9], -1
	s_cbranch_vccnz .LBB0_959
